# workspace pointer kept in v254 lanes (no flat_load at the 11 GEMM phase starts) on top of wave-1 invalidate
# baseline (speedup 1.0000x reference)
.LBB0_124:
	s_or_b64 exec, exec, s[38:39]
	s_mov_b64 s[4:5], s[0:1]
	s_waitcnt lgkmcnt(0)
	s_barrier
	s_load_dwordx2 s[98:99], s[0:1], 0xd8
	v_mov_b32_e32 v10, 0
	v_mov_b32_e32 v11, 0
	s_waitcnt lgkmcnt(0)
	v_writelane_b32 v254, s98, 3
	v_writelane_b32 v254, s99, 4
	global_load_dwordx4 v[0:3], v10, s[98:99] offset:64 sc1
	global_load_dwordx4 v[4:7], v10, s[98:99] offset:80 sc1
	s_waitcnt vmcnt(0)
	v_or3_b32 v8, v0, v1, v2
	v_or3_b32 v8, v8, v3, v4
	v_or3_b32 v8, v8, v5, v6
	v_or_b32_e32 v8, v8, v7
	v_add_u32_e32 v9, -1, v0
	v_and_b32_e32 v9, v9, v0
	v_or_b32_e32 v11, v11, v9
	v_add_u32_e32 v9, -1, v1
	v_and_b32_e32 v9, v9, v1
	v_or_b32_e32 v11, v11, v9
	v_add_u32_e32 v9, -1, v2
	v_and_b32_e32 v9, v9, v2
	v_or_b32_e32 v11, v11, v9
	v_add_u32_e32 v9, -1, v3
	v_and_b32_e32 v9, v9, v3
	v_or_b32_e32 v11, v11, v9
	v_add_u32_e32 v9, -1, v4
	v_and_b32_e32 v9, v9, v4
	v_or_b32_e32 v11, v11, v9
	v_add_u32_e32 v9, -1, v5
	v_and_b32_e32 v9, v9, v5
	v_or_b32_e32 v11, v11, v9
	v_add_u32_e32 v9, -1, v6
	v_and_b32_e32 v9, v9, v6
	v_or_b32_e32 v11, v11, v9
	v_add_u32_e32 v9, -1, v7
	v_and_b32_e32 v9, v9, v7
	v_or_b32_e32 v11, v11, v9
	v_xor_b32_e32 v8, 0xff, v8
	v_or_b32_e32 v8, v8, v11
	s_nop 0
	v_readfirstlane_b32 s98, v8
	s_cmp_eq_u32 s98, 0
	s_cselect_b32 s98, 1, 0
	s_cmp_eq_u32 s68, 0x100
	s_cselect_b32 s98, s98, 0
	v_writelane_b32 v254, s98, 2
	s_cmpk_lt_i32 s2, 0x200
	v_mov_b64_e32 v[0:1], s[4:5]
	v_readlane_b32 s100, v254, 3
	v_readlane_b32 s101, v254, 4
	s_nop 0
	v_mov_b32_e32 v0, s100
	v_mov_b32_e32 v1, s101
	v_mov_b32_e32 v10, v176
	s_cselect_b64 s[46:47], -1, 0
	s_and_b64 vcc, exec, s[46:47]
	v_readfirstlane_b32 s6, v10
	s_cbranch_vccz .LBB0_130
	s_lshr_b32 s3, s33, 29
	s_add_i32 s3, s2, s3
	s_and_b32 s4, s3, -8
	s_sub_i32 s7, s2, s4
	s_cmp_gt_i32 s7, -1
	s_cbranch_scc0 .LBB0_127
	s_lshl_b32 s8, s7, 6
	s_cbranch_execz .LBB0_128
	s_branch .LBB0_129

.LBB0_247:
	s_or_b64 exec, exec, s[48:49]
	s_mov_b64 s[6:7], s[0:1]
	s_waitcnt lgkmcnt(0)
	s_barrier
	s_cmpk_lt_i32 s2, 0x380
	s_waitcnt vmcnt(0)
	v_mov_b64_e32 v[0:1], s[6:7]
	v_readlane_b32 s100, v254, 3
	v_readlane_b32 s101, v254, 4
	s_nop 0
	v_mov_b32_e32 v4, s100
	v_mov_b32_e32 v5, s101
	s_cselect_b64 s[48:49], -1, 0
	s_ashr_i32 s69, s68, 31
	v_mov_b32_e32 v14, v176
	s_cmpk_gt_i32 s2, 0x37f
	s_nop 0
	v_readfirstlane_b32 s6, v14
	s_cbranch_scc1 .LBB0_268
	s_lshr_b32 s3, s33, 29
	s_add_i32 s3, s2, s3
	s_ashr_i32 s7, s3, 3
	s_and_b32 s3, s3, -8
	s_sub_i32 s3, s2, s3
	s_cmp_lt_i32 s3, 0
	s_movk_i32 s10, 0x71
	s_cselect_b32 s10, s10, 0x70
	s_mul_i32 s3, s10, s3
	s_add_i32 s3, s3, s7
	s_mul_hi_i32 s7, s3, 0x92492493
	s_add_i32 s7, s7, s3
	s_lshr_b32 s10, s7, 31
	s_ashr_i32 s7, s7, 5
	s_add_i32 s7, s7, s10
	s_lshl_b32 s10, s7, 3
	s_mul_i32 s7, s7, 56
	s_sub_i32 s3, s3, s7
	s_bfe_i32 s7, s3, 0x80000
	s_bfe_u32 s7, s7, 0x3000c
	s_add_i32 s11, s3, s7
	s_bfe_i32 s7, s11, 0x80000
	s_and_b32 s11, s11, 0xf8
	s_sub_i32 s3, s3, s11
	s_sext_i32_i8 s3, s3
	s_sext_i32_i16 s7, s7
	s_add_i32 s30, s10, s3
	s_mov_b64 s[8:9], 0x1a100000
	s_lshr_b32 s7, s7, 3
	s_ashr_i32 s31, s30, 31
	v_readfirstlane_b32 s3, v176
	s_cmpk_gt_u32 s3, 0xff
	s_waitcnt vmcnt(0) lgkmcnt(0)
	v_lshl_add_u64 v[128:129], v[4:5], 0, s[8:9]
	s_cbranch_scc1 .LBB0_250
	s_lshl_b64 s[8:9], s[30:31], 8
	s_and_b32 s10, s3, 0xc0
	s_lshl_b32 s3, s3, 4
	s_or_b32 s8, s8, s10
	s_and_b32 s3, s3, 0xc00
	v_mov_b32_e32 v1, s9
	v_or_b32_e32 v0, s8, v177
	s_add_i32 s3, s3, 0
	v_lshl_add_u64 v[0:1], v[0:1], 4, v[128:129]
	s_add_i32 m0, s3, 0x21c00
	s_nop 0
	global_load_lds_dwordx4 v[0:1], off

.Lrm_done_lru_9673:
	s_mov_b32 s10, s68
	s_waitcnt lgkmcnt(0)
	s_barrier
	v_writelane_b32 v255, s3, 0
	v_writelane_b32 v255, s10, 1
	v_writelane_b32 v255, s11, 2
	v_writelane_b32 v255, s12, 3
	v_writelane_b32 v255, s13, 4
	v_writelane_b32 v255, s14, 5
	v_writelane_b32 v255, s15, 6
	v_writelane_b32 v255, s16, 7
	v_writelane_b32 v255, s17, 8
	v_writelane_b32 v255, s20, 9
	v_writelane_b32 v255, s21, 10
	v_writelane_b32 v255, s28, 11
	v_writelane_b32 v255, s30, 12
	v_writelane_b32 v255, s34, 13
	v_writelane_b32 v255, s38, 14
	v_writelane_b32 v255, s48, 15
	v_writelane_b32 v255, s49, 16
	v_writelane_b32 v255, s52, 17
	v_writelane_b32 v255, s53, 18
	v_writelane_b32 v255, s54, 19
	v_writelane_b32 v255, s56, 20
	v_writelane_b32 v255, s57, 21
	v_writelane_b32 v255, s69, 22
	s_add_i32 s2, s2, 0x300
	s_mov_b64 s[6:7], s[0:1]
	s_cmpk_lt_i32 s2, 0x380
	s_waitcnt vmcnt(0)
	v_mov_b64_e32 v[0:1], s[6:7]
	v_readlane_b32 s100, v254, 3
	v_readlane_b32 s101, v254, 4
	s_nop 0
	v_mov_b32_e32 v4, s100
	v_mov_b32_e32 v5, s101
	s_cselect_b64 s[48:49], -1, 0
	s_ashr_i32 s69, s68, 31
	v_mov_b32_e32 v14, v176
	s_cmpk_gt_i32 s2, 0x37f
	s_nop 0
	v_readfirstlane_b32 s6, v14
	s_cbranch_scc1 .Lwb0_after
	s_lshr_b32 s3, s33, 29
	s_add_i32 s3, s2, s3
	s_ashr_i32 s7, s3, 3
	s_and_b32 s3, s3, -8
	s_sub_i32 s3, s2, s3
	s_cmp_lt_i32 s3, 0
	s_movk_i32 s10, 0x71
	s_cselect_b32 s10, s10, 0x70
	s_mul_i32 s3, s10, s3
	s_add_i32 s3, s3, s7
	s_mul_hi_i32 s7, s3, 0x92492493
	s_add_i32 s7, s7, s3
	s_lshr_b32 s10, s7, 31
	s_ashr_i32 s7, s7, 5
	s_add_i32 s7, s7, s10
	s_lshl_b32 s10, s7, 3
	s_mul_i32 s7, s7, 56
	s_sub_i32 s3, s3, s7
	s_bfe_i32 s7, s3, 0x80000
	s_bfe_u32 s7, s7, 0x3000c
	s_add_i32 s11, s3, s7
	s_bfe_i32 s7, s11, 0x80000
	s_and_b32 s11, s11, 0xf8
	s_sub_i32 s3, s3, s11
	s_sext_i32_i8 s3, s3
	s_sext_i32_i16 s7, s7
	s_add_i32 s30, s10, s3
	s_mov_b64 s[8:9], 0x1a100000
	s_lshr_b32 s7, s7, 3
	s_ashr_i32 s31, s30, 31
	v_readfirstlane_b32 s3, v176
	s_cmpk_gt_u32 s3, 0xff
	s_waitcnt vmcnt(0) lgkmcnt(0)
	v_lshl_add_u64 v[128:129], v[4:5], 0, s[8:9]
	s_cbranch_scc1 .Lwb0_BB0_250
	s_lshl_b64 s[8:9], s[30:31], 8
	s_and_b32 s10, s3, 0xc0
	s_lshl_b32 s3, s3, 4
	s_or_b32 s8, s8, s10
	s_and_b32 s3, s3, 0xc00
	v_mov_b32_e32 v1, s9
	v_or_b32_e32 v0, s8, v177
	s_add_i32 s3, s3, 0
	v_lshl_add_u64 v[0:1], v[0:1], 4, v[128:129]
	s_add_i32 m0, s3, 0x21c00
	s_nop 0
	global_load_lds_dwordx4 v[0:1], off

.LBB0_489:
	s_or_b64 exec, exec, s[50:51]
	s_mov_b64 s[6:7], s[0:1]
	s_waitcnt lgkmcnt(0)
	s_barrier
	v_mov_b32_e32 v12, v176
	s_waitcnt vmcnt(0)
	v_mov_b64_e32 v[0:1], s[6:7]
	v_readlane_b32 s100, v254, 3
	v_readlane_b32 s101, v254, 4
	s_nop 0
	v_mov_b32_e32 v0, s100
	v_mov_b32_e32 v1, s101
	s_and_b64 vcc, exec, s[46:47]
	v_readfirstlane_b32 s10, v12
	s_cbranch_vccz .LBB0_495
	s_lshr_b32 s3, s33, 29
	s_add_i32 s3, s2, s3
	s_and_b32 s6, s3, -8
	s_sub_i32 s8, s2, s6
	s_cmp_gt_i32 s8, -1
	s_cbranch_scc0 .LBB0_492
	s_lshl_b32 s9, s8, 6
	s_cbranch_execz .LBB0_493
	s_branch .LBB0_494

.LBB0_608:
	s_or_b64 exec, exec, s[50:51]
	s_mov_b64 s[6:7], s[0:1]
	s_waitcnt lgkmcnt(0)
	s_barrier
	v_mov_b32_e32 v14, v176
	s_waitcnt vmcnt(0)
	v_mov_b64_e32 v[0:1], s[6:7]
	v_readlane_b32 s100, v254, 3
	v_readlane_b32 s101, v254, 4
	s_nop 0
	v_mov_b32_e32 v4, s100
	v_mov_b32_e32 v5, s101
	v_cndmask_b32_e64 v0, 0, 1, s[40:41]
	v_cmp_ne_u32_e64 s[6:7], 1, v0
	s_andn2_b64 vcc, exec, s[40:41]
	v_readfirstlane_b32 s8, v14
	s_cbranch_vccnz .LBB0_629
	s_lshr_b32 s3, s33, 29
	s_add_i32 s3, s2, s3
	s_ashr_i32 s9, s3, 3
	s_and_b32 s3, s3, -8
	s_sub_i32 s3, s2, s3
	s_cmp_lt_i32 s3, 0
	s_movk_i32 s12, 0x161
	s_cselect_b32 s12, s12, 0x160
	s_mul_i32 s3, s12, s3
	s_add_i32 s3, s3, s9
	s_mul_hi_i32 s9, s3, 0x2e8ba2e9
	s_lshr_b32 s12, s9, 31
	s_ashr_i32 s9, s9, 5
	s_add_i32 s9, s9, s12
	s_lshl_b32 s12, s9, 3
	s_mulk_i32 s9, 0xb0
	s_sub_i32 s9, s3, s9
	s_sext_i32_i16 s3, s9
	s_bfe_u32 s3, s3, 0x3001c
	s_add_i32 s13, s9, s3
	s_sext_i32_i16 s3, s13
	s_and_b32 s13, s13, 0xfff8
	s_sub_i32 s9, s9, s13
	s_sext_i32_i16 s9, s9
	s_add_i32 s34, s12, s9
	s_mov_b64 s[10:11], 0x1a100000
	s_lshr_b32 s3, s3, 3
	s_ashr_i32 s35, s34, 31
	v_readfirstlane_b32 s9, v176
	s_cmpk_gt_u32 s9, 0xff
	s_waitcnt vmcnt(0) lgkmcnt(0)
	v_lshl_add_u64 v[128:129], v[4:5], 0, s[10:11]
	s_cbranch_scc1 .LBB0_611
	s_lshl_b64 s[10:11], s[34:35], 8
	s_and_b32 s12, s9, 0xc0
	s_lshl_b32 s9, s9, 4
	s_or_b32 s10, s10, s12
	s_and_b32 s9, s9, 0xc00
	v_mov_b32_e32 v1, s11
	v_or_b32_e32 v0, s10, v177
	s_add_i32 s9, s9, 0
	v_lshl_add_u64 v[0:1], v[0:1], 4, v[128:129]
	s_add_i32 m0, s9, 0x21c00
	s_nop 0
	global_load_lds_dwordx4 v[0:1], off

.LBB0_673:
	s_or_b64 exec, exec, s[50:51]
	s_mov_b64 s[8:9], s[0:1]
	s_waitcnt lgkmcnt(0)
	s_barrier
	v_mov_b32_e32 v10, v176
	v_mov_b64_e32 v[0:1], s[8:9]
	v_readlane_b32 s100, v254, 3
	v_readlane_b32 s101, v254, 4
	s_nop 0
	v_mov_b32_e32 v0, s100
	v_mov_b32_e32 v1, s101
	s_and_b64 vcc, exec, s[46:47]
	v_readfirstlane_b32 s10, v10
	s_cbranch_vccz .LBB0_679
	s_lshr_b32 s3, s33, 29
	s_add_i32 s3, s2, s3
	s_and_b32 s8, s3, -8
	s_sub_i32 s11, s2, s8
	s_cmp_gt_i32 s11, -1
	s_cbranch_scc0 .LBB0_676
	s_lshl_b32 s12, s11, 6
	s_cbranch_execz .LBB0_677
	s_branch .LBB0_678

.LBB0_796:
	s_or_b64 exec, exec, s[50:51]
	s_mov_b64 s[8:9], s[0:1]
	s_waitcnt lgkmcnt(0)
	s_barrier
	v_mov_b32_e32 v14, v176
	s_waitcnt vmcnt(0)
	v_mov_b64_e32 v[0:1], s[8:9]
	v_readlane_b32 s100, v254, 3
	v_readlane_b32 s101, v254, 4
	s_nop 0
	v_mov_b32_e32 v4, s100
	v_mov_b32_e32 v5, s101
	s_and_b64 vcc, exec, s[6:7]
	v_readfirstlane_b32 s8, v14
	s_cbranch_vccnz .LBB0_817
	s_lshr_b32 s3, s33, 29
	s_add_i32 s3, s2, s3
	s_ashr_i32 s9, s3, 3
	s_and_b32 s3, s3, -8
	s_sub_i32 s3, s2, s3
	s_cmp_lt_i32 s3, 0
	s_movk_i32 s12, 0x161
	s_cselect_b32 s12, s12, 0x160
	s_mul_i32 s3, s12, s3
	s_add_i32 s3, s3, s9
	s_mul_hi_i32 s9, s3, 0x2e8ba2e9
	s_lshr_b32 s12, s9, 31
	s_ashr_i32 s9, s9, 5
	s_add_i32 s9, s9, s12
	s_lshl_b32 s12, s9, 3
	s_mulk_i32 s9, 0xb0
	s_sub_i32 s9, s3, s9
	s_sext_i32_i16 s3, s9
	s_bfe_u32 s3, s3, 0x3001c
	s_add_i32 s13, s9, s3
	s_sext_i32_i16 s3, s13
	s_and_b32 s13, s13, 0xfff8
	s_sub_i32 s9, s9, s13
	s_sext_i32_i16 s9, s9
	s_add_i32 s34, s12, s9
	s_mov_b64 s[10:11], 0x1a100000
	s_lshr_b32 s3, s3, 3
	s_ashr_i32 s35, s34, 31
	v_readfirstlane_b32 s9, v176
	s_cmpk_gt_u32 s9, 0xff
	s_waitcnt vmcnt(0) lgkmcnt(0)
	v_lshl_add_u64 v[128:129], v[4:5], 0, s[10:11]
	s_cbranch_scc1 .LBB0_799
	s_lshl_b64 s[10:11], s[34:35], 8
	s_and_b32 s12, s9, 0xc0
	s_lshl_b32 s9, s9, 4
	s_or_b32 s10, s10, s12
	s_and_b32 s9, s9, 0xc00
	v_mov_b32_e32 v1, s11
	v_or_b32_e32 v0, s10, v177
	s_add_i32 s9, s9, 0
	v_lshl_add_u64 v[0:1], v[0:1], 4, v[128:129]
	s_add_i32 m0, s9, 0x21c00
	s_nop 0
	global_load_lds_dwordx4 v[0:1], off

.LBB0_984:
	s_or_b64 exec, exec, s[50:51]
	s_mov_b64 s[8:9], s[0:1]
	s_waitcnt lgkmcnt(0)
	s_barrier
	v_mov_b32_e32 v14, v176
	s_waitcnt vmcnt(0)
	v_mov_b64_e32 v[0:1], s[8:9]
	v_readlane_b32 s100, v254, 3
	v_readlane_b32 s101, v254, 4
	s_nop 0
	v_mov_b32_e32 v4, s100
	v_mov_b32_e32 v5, s101
	s_andn2_b64 vcc, exec, s[48:49]
	v_readfirstlane_b32 s8, v14
	s_cbranch_vccnz .LBB0_1005
	s_lshr_b32 s3, s33, 29
	s_add_i32 s3, s2, s3
	s_ashr_i32 s9, s3, 3
	s_and_b32 s3, s3, -8
	s_sub_i32 s3, s2, s3
	s_cmp_lt_i32 s3, 0
	s_movk_i32 s12, 0x71
	s_cselect_b32 s12, s12, 0x70
	s_mul_i32 s3, s12, s3
	s_add_i32 s3, s3, s9
	s_mul_hi_i32 s9, s3, 0x92492493
	s_add_i32 s9, s9, s3
	s_lshr_b32 s12, s9, 31
	s_ashr_i32 s9, s9, 5
	s_add_i32 s9, s9, s12
	s_lshl_b32 s12, s9, 3
	s_mul_i32 s9, s9, 56
	s_sub_i32 s3, s3, s9
	s_bfe_i32 s9, s3, 0x80000
	s_bfe_u32 s9, s9, 0x3000c
	s_add_i32 s13, s3, s9
	s_bfe_i32 s9, s13, 0x80000
	s_and_b32 s13, s13, 0xf8
	s_sub_i32 s3, s3, s13
	s_sext_i32_i8 s3, s3
	s_sext_i32_i16 s9, s9
	s_add_i32 s34, s12, s3
	s_mov_b64 s[10:11], 0x1a100000
	s_lshr_b32 s9, s9, 3
	s_ashr_i32 s35, s34, 31
	v_readfirstlane_b32 s3, v176
	s_cmpk_gt_u32 s3, 0xff
	s_waitcnt vmcnt(0) lgkmcnt(0)
	v_lshl_add_u64 v[128:129], v[4:5], 0, s[10:11]
	s_cbranch_scc1 .LBB0_987
	s_lshl_b64 s[10:11], s[34:35], 8
	s_and_b32 s12, s3, 0xc0
	s_lshl_b32 s3, s3, 4
	s_or_b32 s10, s10, s12
	s_and_b32 s3, s3, 0xc00
	v_mov_b32_e32 v1, s11
	v_or_b32_e32 v0, s10, v177
	s_add_i32 s3, s3, 0
	v_lshl_add_u64 v[0:1], v[0:1], 4, v[128:129]
	s_add_i32 m0, s3, 0x21c00
	s_nop 0
	global_load_lds_dwordx4 v[0:1], off

.Lrm_done_lru_31452:
	s_waitcnt lgkmcnt(0)
	s_barrier
	v_writelane_b32 v255, s3, 0
	v_writelane_b32 v255, s12, 1
	v_writelane_b32 v255, s13, 2
	v_writelane_b32 v255, s14, 3
	v_writelane_b32 v255, s15, 4
	v_writelane_b32 v255, s16, 5
	v_writelane_b32 v255, s17, 6
	v_writelane_b32 v255, s21, 7
	v_writelane_b32 v255, s22, 8
	v_writelane_b32 v255, s23, 9
	v_writelane_b32 v255, s28, 10
	v_writelane_b32 v255, s34, 11
	v_writelane_b32 v255, s50, 12
	s_add_i32 s2, s2, 0x300
	s_mov_b64 s[8:9], s[0:1]
	s_cmpk_lt_i32 s2, 0x380
	s_cselect_b64 s[48:49], -1, 0
	v_mov_b32_e32 v14, v176
	s_waitcnt vmcnt(0)
	v_mov_b64_e32 v[0:1], s[8:9]
	v_readlane_b32 s100, v254, 3
	v_readlane_b32 s101, v254, 4
	s_nop 0
	v_mov_b32_e32 v4, s100
	v_mov_b32_e32 v5, s101
	s_andn2_b64 vcc, exec, s[48:49]
	v_readfirstlane_b32 s8, v14
	s_cbranch_vccnz .Lwb1_after
	s_lshr_b32 s3, s33, 29
	s_add_i32 s3, s2, s3
	s_ashr_i32 s9, s3, 3
	s_and_b32 s3, s3, -8
	s_sub_i32 s3, s2, s3
	s_cmp_lt_i32 s3, 0
	s_movk_i32 s12, 0x71
	s_cselect_b32 s12, s12, 0x70
	s_mul_i32 s3, s12, s3
	s_add_i32 s3, s3, s9
	s_mul_hi_i32 s9, s3, 0x92492493
	s_add_i32 s9, s9, s3
	s_lshr_b32 s12, s9, 31
	s_ashr_i32 s9, s9, 5
	s_add_i32 s9, s9, s12
	s_lshl_b32 s12, s9, 3
	s_mul_i32 s9, s9, 56
	s_sub_i32 s3, s3, s9
	s_bfe_i32 s9, s3, 0x80000
	s_bfe_u32 s9, s9, 0x3000c
	s_add_i32 s13, s3, s9
	s_bfe_i32 s9, s13, 0x80000
	s_and_b32 s13, s13, 0xf8
	s_sub_i32 s3, s3, s13
	s_sext_i32_i8 s3, s3
	s_sext_i32_i16 s9, s9
	s_add_i32 s34, s12, s3
	s_mov_b64 s[10:11], 0x1a100000
	s_lshr_b32 s9, s9, 3
	s_ashr_i32 s35, s34, 31
	v_readfirstlane_b32 s3, v176
	s_cmpk_gt_u32 s3, 0xff
	s_waitcnt vmcnt(0) lgkmcnt(0)
	v_lshl_add_u64 v[128:129], v[4:5], 0, s[10:11]
	s_cbranch_scc1 .Lwb1_BB0_987
	s_lshl_b64 s[10:11], s[34:35], 8
	s_and_b32 s12, s3, 0xc0
	s_lshl_b32 s3, s3, 4
	s_or_b32 s10, s10, s12
	s_and_b32 s3, s3, 0xc00
	v_mov_b32_e32 v1, s11
	v_or_b32_e32 v0, s10, v177
	s_add_i32 s3, s3, 0
	v_lshl_add_u64 v[0:1], v[0:1], 4, v[128:129]
	s_add_i32 m0, s3, 0x21c00
	s_nop 0
	global_load_lds_dwordx4 v[0:1], off

.LBB0_1226:
	s_or_b64 exec, exec, s[48:49]
	s_mov_b64 s[8:9], s[0:1]
	s_waitcnt lgkmcnt(0)
	s_barrier
	v_mov_b32_e32 v12, v176
	s_waitcnt vmcnt(0)
	v_mov_b64_e32 v[0:1], s[8:9]
	v_readlane_b32 s100, v254, 3
	v_readlane_b32 s101, v254, 4
	s_nop 0
	v_mov_b32_e32 v0, s100
	v_mov_b32_e32 v1, s101
	s_and_b64 vcc, exec, s[46:47]
	v_readfirstlane_b32 s10, v12
	s_cbranch_vccz .LBB0_1232
	s_lshr_b32 s3, s33, 29
	s_add_i32 s3, s2, s3
	s_and_b32 s8, s3, -8
	s_sub_i32 s11, s2, s8
	s_cmp_gt_i32 s11, -1
	s_cbranch_scc0 .LBB0_1229
	s_lshl_b32 s12, s11, 6
	s_cbranch_execz .LBB0_1230
	s_branch .LBB0_1231

.LBB0_1345:
	s_or_b64 exec, exec, s[48:49]
	s_mov_b64 s[8:9], s[0:1]
	s_waitcnt lgkmcnt(0)
	s_barrier
	v_mov_b32_e32 v14, v176
	s_waitcnt vmcnt(0)
	v_mov_b64_e32 v[0:1], s[8:9]
	v_readlane_b32 s100, v254, 3
	v_readlane_b32 s101, v254, 4
	s_nop 0
	v_mov_b32_e32 v4, s100
	v_mov_b32_e32 v5, s101
	s_and_b64 vcc, exec, s[6:7]
	v_readfirstlane_b32 s6, v14
	s_cbranch_vccnz .LBB0_1366
	s_lshr_b32 s3, s33, 29
	s_add_i32 s3, s2, s3
	s_ashr_i32 s7, s3, 3
	s_and_b32 s3, s3, -8
	s_sub_i32 s3, s2, s3
	s_cmp_lt_i32 s3, 0
	s_movk_i32 s10, 0x161
	s_cselect_b32 s10, s10, 0x160
	s_mul_i32 s3, s10, s3
	s_add_i32 s3, s3, s7
	s_mul_hi_i32 s7, s3, 0x2e8ba2e9
	s_lshr_b32 s10, s7, 31
	s_ashr_i32 s7, s7, 5
	s_add_i32 s7, s7, s10
	s_lshl_b32 s10, s7, 3
	s_mulk_i32 s7, 0xb0
	s_sub_i32 s7, s3, s7
	s_sext_i32_i16 s3, s7
	s_bfe_u32 s3, s3, 0x3001c
	s_add_i32 s11, s7, s3
	s_sext_i32_i16 s3, s11
	s_and_b32 s11, s11, 0xfff8
	s_sub_i32 s7, s7, s11
	s_sext_i32_i16 s7, s7
	s_add_i32 s30, s10, s7
	s_mov_b64 s[8:9], 0x1a100000
	s_lshr_b32 s3, s3, 3
	s_ashr_i32 s31, s30, 31
	v_readfirstlane_b32 s7, v176
	s_cmpk_gt_u32 s7, 0xff
	s_waitcnt vmcnt(0) lgkmcnt(0)
	v_lshl_add_u64 v[128:129], v[4:5], 0, s[8:9]
	s_cbranch_scc1 .LBB0_1348
	s_lshl_b64 s[8:9], s[30:31], 8
	s_and_b32 s10, s7, 0xc0
	s_lshl_b32 s7, s7, 4
	s_or_b32 s8, s8, s10
	s_and_b32 s7, s7, 0xc00
	v_mov_b32_e32 v1, s9
	v_or_b32_e32 v0, s8, v177
	s_add_i32 s7, s7, 0
	v_lshl_add_u64 v[0:1], v[0:1], 4, v[128:129]
	s_add_i32 m0, s7, 0x21c00
	s_nop 0
	global_load_lds_dwordx4 v[0:1], off

.LBB0_1410:
	s_or_b64 exec, exec, s[38:39]
	s_mov_b64 s[6:7], s[0:1]
	s_waitcnt lgkmcnt(0)
	s_barrier
	s_and_b64 vcc, exec, s[46:47]
	v_mov_b64_e32 v[0:1], s[6:7]
	v_readlane_b32 s100, v254, 3
	v_readlane_b32 s101, v254, 4
	s_nop 0
	v_mov_b32_e32 v0, s100
	v_mov_b32_e32 v1, s101
	s_nop 0
	v_readfirstlane_b32 s13, v176
	s_cbranch_vccz .LBB0_1413
	s_lshr_b32 s3, s33, 29
	s_add_i32 s9, s2, s3
	s_and_b32 s3, s9, -8
	s_sub_i32 s3, s2, s3
	s_cmp_gt_i32 s3, -1
	s_cbranch_scc0 .LBB0_1468
	s_lshl_b32 s8, s3, 6
	s_ashr_i32 s6, s9, 3
	s_cbranch_execz .LBB0_1469
	s_branch .LBB0_1470
